# stack2 + scan2 step: six b128 fragment reads hoisted up front with counted lgkmcnt waits
# baseline (speedup 1.0000x reference)
.LBB0_663:
	s_add_i32 s11, s27, s36
	s_add_i32 s30, s11, -8
	s_ashr_i32 s31, s30, 31
	s_lshl_b64 s[30:31], s[30:31], 13
	v_lshl_add_u64 v[74:75], v[62:63], 0, s[30:31]
	v_cvt_pk_bf16_f32 v0, v36, s0
	global_store_short v[74:75], v0, off
	v_cvt_pk_bf16_f32 v0, v37, s0
	global_store_short v[74:75], v0, off offset:128
	v_cvt_pk_bf16_f32 v0, v38, s0
	global_store_short v[74:75], v0, off offset:256
	v_cvt_pk_bf16_f32 v0, v39, s0
	global_store_short v[74:75], v0, off offset:384
	v_add_u32_e32 v0, v66, v72
	ds_read2st64_b32 v[36:37], v0 offset0:72 offset1:73
	ds_read_b32 v38, v0 offset:18944
	v_add_u32_e32 v0, v66, v73
	ds_read_b32 v39, v0 offset:18432
	ds_read_b128 v[74:77], v67
	ds_read_b128 v[78:81], v68 offset:26624
	ds_read_b128 v[82:85], v68 offset:28928
	ds_read_b128 v[86:89], v67 offset:64
	ds_read_b128 v[90:93], v68 offset:26688
	ds_read_b128 v[94:97], v68 offset:28992
	s_waitcnt lgkmcnt(4)
	v_mfma_f32_16x16x32_bf16 v[36:39], v[78:81], v[74:77], v[36:39]
	s_waitcnt lgkmcnt(3)
	v_mfma_f32_16x16x32_bf16 v[36:39], v[82:85], v[74:77], v[36:39]
	s_waitcnt lgkmcnt(1)
	v_mfma_f32_16x16x32_bf16 v[36:39], v[90:93], v[86:89], v[36:39]
	s_waitcnt lgkmcnt(0)
	v_mfma_f32_16x16x32_bf16 v[36:39], v[94:97], v[86:89], v[36:39]

.LBB0_670:
	s_add_i32 s11, s27, s36
	s_add_i32 s30, s11, -7
	s_ashr_i32 s31, s30, 31
	s_lshl_b64 s[30:31], s[30:31], 13
	v_lshl_add_u64 v[74:75], v[62:63], 0, s[30:31]
	v_cvt_pk_bf16_f32 v0, v36, s0
	global_store_short v[74:75], v0, off
	v_cvt_pk_bf16_f32 v0, v37, s0
	global_store_short v[74:75], v0, off offset:128
	v_cvt_pk_bf16_f32 v0, v38, s0
	global_store_short v[74:75], v0, off offset:256
	v_cvt_pk_bf16_f32 v0, v39, s0
	global_store_short v[74:75], v0, off offset:384
	v_add_u32_e32 v0, v69, v72
	ds_read2st64_b32 v[36:37], v0 offset0:88 offset1:89
	ds_read_b32 v38, v0 offset:23040
	v_add_u32_e32 v0, v69, v73
	ds_read_b32 v39, v0 offset:22528
	ds_read_b128 v[74:77], v67 offset:9216
	ds_read_b128 v[78:81], v68 offset:26624
	ds_read_b128 v[82:85], v68 offset:28928
	ds_read_b128 v[86:89], v67 offset:9280
	ds_read_b128 v[90:93], v68 offset:26688
	ds_read_b128 v[94:97], v68 offset:28992
	s_waitcnt lgkmcnt(4)
	v_mfma_f32_16x16x32_bf16 v[36:39], v[78:81], v[74:77], v[36:39]
	s_waitcnt lgkmcnt(3)
	v_mfma_f32_16x16x32_bf16 v[36:39], v[82:85], v[74:77], v[36:39]
	s_waitcnt lgkmcnt(1)
	v_mfma_f32_16x16x32_bf16 v[36:39], v[90:93], v[86:89], v[36:39]
	s_waitcnt lgkmcnt(0)
	v_mfma_f32_16x16x32_bf16 v[36:39], v[94:97], v[86:89], v[36:39]

.LBB0_677:
	s_add_i32 s11, s27, s36
	s_add_i32 s30, s11, -6
	s_ashr_i32 s31, s30, 31
	s_lshl_b64 s[30:31], s[30:31], 13
	v_lshl_add_u64 v[74:75], v[62:63], 0, s[30:31]
	v_cvt_pk_bf16_f32 v0, v36, s0
	global_store_short v[74:75], v0, off
	v_cvt_pk_bf16_f32 v0, v37, s0
	global_store_short v[74:75], v0, off offset:128
	v_cvt_pk_bf16_f32 v0, v38, s0
	global_store_short v[74:75], v0, off offset:256
	v_cvt_pk_bf16_f32 v0, v39, s0
	global_store_short v[74:75], v0, off offset:384
	v_add_u32_e32 v0, v66, v72
	ds_read2st64_b32 v[36:37], v0 offset0:72 offset1:73
	ds_read_b32 v38, v0 offset:18944
	v_add_u32_e32 v0, v66, v73
	ds_read_b32 v39, v0 offset:18432
	ds_read_b128 v[74:77], v67
	ds_read_b128 v[78:81], v68 offset:26624
	ds_read_b128 v[82:85], v68 offset:28928
	ds_read_b128 v[86:89], v67 offset:64
	ds_read_b128 v[90:93], v68 offset:26688
	ds_read_b128 v[94:97], v68 offset:28992
	s_waitcnt lgkmcnt(4)
	v_mfma_f32_16x16x32_bf16 v[36:39], v[78:81], v[74:77], v[36:39]
	s_waitcnt lgkmcnt(3)
	v_mfma_f32_16x16x32_bf16 v[36:39], v[82:85], v[74:77], v[36:39]
	s_waitcnt lgkmcnt(1)
	v_mfma_f32_16x16x32_bf16 v[36:39], v[90:93], v[86:89], v[36:39]
	s_waitcnt lgkmcnt(0)
	v_mfma_f32_16x16x32_bf16 v[36:39], v[94:97], v[86:89], v[36:39]

.LBB0_684:
	s_add_i32 s11, s27, s36
	s_add_i32 s28, s11, -5
	s_ashr_i32 s29, s28, 31
	s_lshl_b64 s[28:29], s[28:29], 13
	v_lshl_add_u64 v[74:75], v[62:63], 0, s[28:29]
	v_cvt_pk_bf16_f32 v0, v36, s0
	global_store_short v[74:75], v0, off
	v_cvt_pk_bf16_f32 v0, v37, s0
	global_store_short v[74:75], v0, off offset:128
	v_cvt_pk_bf16_f32 v0, v38, s0
	global_store_short v[74:75], v0, off offset:256
	v_cvt_pk_bf16_f32 v0, v39, s0
	global_store_short v[74:75], v0, off offset:384
	v_add_u32_e32 v0, v69, v72
	ds_read2st64_b32 v[36:37], v0 offset0:88 offset1:89
	ds_read_b32 v38, v0 offset:23040
	v_add_u32_e32 v0, v69, v73
	ds_read_b32 v39, v0 offset:22528
	ds_read_b128 v[74:77], v67 offset:9216
	ds_read_b128 v[78:81], v68 offset:26624
	ds_read_b128 v[82:85], v68 offset:28928
	ds_read_b128 v[86:89], v67 offset:9280
	ds_read_b128 v[90:93], v68 offset:26688
	ds_read_b128 v[94:97], v68 offset:28992
	s_waitcnt lgkmcnt(4)
	v_mfma_f32_16x16x32_bf16 v[36:39], v[78:81], v[74:77], v[36:39]
	s_waitcnt lgkmcnt(3)
	v_mfma_f32_16x16x32_bf16 v[36:39], v[82:85], v[74:77], v[36:39]
	s_waitcnt lgkmcnt(1)
	v_mfma_f32_16x16x32_bf16 v[36:39], v[90:93], v[86:89], v[36:39]
	s_waitcnt lgkmcnt(0)
	v_mfma_f32_16x16x32_bf16 v[36:39], v[94:97], v[86:89], v[36:39]
